# code placement: GEMM K-loop heads padded to 64-byte boundaries
# speedup vs baseline: 1.0057x; 1.0057x over previous
.LBB0_223:
	v_add_u32_e32 v155, s81, v17
	v_add_u32_e32 v156, 0x2000, v155
	v_readfirstlane_b32 s17, v155
	v_lshl_add_u64 v[4:5], v[4:5], 0, s[6:7]
	s_mov_b32 m0, s17
	v_readfirstlane_b32 s17, v156
	v_add_u32_e32 v157, 0x8000, v148
	s_waitcnt vmcnt(4)
	s_barrier
	global_load_lds_dwordx4 v[4:5], off
	v_lshl_add_u64 v[4:5], v[6:7], 0, s[6:7]
	s_mov_b32 m0, s17
	v_readfirstlane_b32 s17, v157
	v_add_u32_e32 v158, 0xa000, v148
	global_load_lds_dwordx4 v[4:5], off
	v_lshl_add_u64 v[4:5], v[8:9], 0, s[6:7]
	s_mov_b32 m0, s17
	v_readfirstlane_b32 s17, v158
	v_add_u32_e32 v159, s82, v17
	global_load_lds_dwordx4 v[4:5], off
	v_lshl_add_u64 v[4:5], v[10:11], 0, s[6:7]
	s_mov_b32 m0, s17
	v_readfirstlane_b32 s17, v159
	v_add_u32_e32 v160, 0x2000, v159
	global_load_lds_dwordx4 v[4:5], off
	v_lshl_add_u64 v[4:5], v[12:13], 0, s[6:7]
	s_mov_b32 m0, s17
	v_readfirstlane_b32 s17, v160
	global_load_lds_dwordx4 v[4:5], off
	v_lshl_add_u64 v[4:5], v[14:15], 0, s[6:7]
	s_mov_b32 m0, s17
	v_and_b32_e32 v18, 15, v16
	global_load_lds_dwordx4 v[4:5], off
	v_lshlrev_b32_e32 v5, 2, v16
	v_and_b32_e32 v19, 48, v16
	v_lshlrev_b32_e32 v4, 6, v18
	v_and_b32_e32 v5, 32, v5
	v_bitop3_b32 v4, v4, v5, v19 bitop3:0x36
	v_add_u32_e32 v6, s33, v4
	v_add_u32_e32 v7, s80, v4
	v_add_u32_e32 v8, s81, v4
	v_add_u32_e32 v9, s82, v4
	s_lshl_b32 s60, s1, 13
	v_add_u32_e32 v10, 0, v4
	v_lshlrev_b32_e32 v4, 6, v16
	s_movk_i32 s1, 0x3c0
	v_and_or_b32 v4, v4, s1, v19
	v_xad_u32 v161, v4, v5, 0
	v_lshl_add_u64 v[4:5], s[24:25], 0, v[130:131]
	v_readlane_b32 s64, v254, 60
	v_lshl_add_u64 v[4:5], v[4:5], 0, v[0:1]
	v_readlane_b32 s76, v253, 8
	v_readlane_b32 s77, v253, 9
	v_readlane_b32 s65, v254, 61
	v_readlane_b32 s66, v254, 62
	v_lshl_add_u64 v[136:137], s[76:77], 0, v[4:5]
	v_lshl_add_u64 v[4:5], s[24:25], 0, v[134:135]
	v_readlane_b32 s67, v254, 63
	v_readlane_b32 s68, v253, 0
	v_readlane_b32 s69, v253, 1
	v_readlane_b32 s70, v253, 2
	v_readlane_b32 s71, v253, 3
	v_readlane_b32 s72, v253, 4
	v_readlane_b32 s73, v253, 5
	v_readlane_b32 s74, v253, 6
	v_readlane_b32 s75, v253, 7
	v_readlane_b32 s78, v253, 10
	v_readlane_b32 s79, v253, 11
	v_lshl_add_u64 v[4:5], v[4:5], 0, v[2:3]
	v_lshl_add_u64 v[138:139], s[76:77], 0, v[4:5]
	v_lshl_add_u64 v[4:5], s[34:35], 0, v[130:131]
	v_readlane_b32 s64, v254, 12
	v_lshl_add_u64 v[0:1], v[4:5], 0, v[0:1]
	v_readlane_b32 s68, v254, 16
	v_readlane_b32 s69, v254, 17
	s_waitcnt vmcnt(6)
	s_lshl_b32 s17, s88, 6
	s_and_b32 s59, s17, 0x3000
	v_lshl_add_u64 v[140:141], s[68:69], 0, v[0:1]
	v_lshl_add_u64 v[0:1], s[34:35], 0, v[134:135]
	v_lshl_add_u64 v[0:1], v[0:1], 0, v[2:3]
	v_lshl_add_u64 v[142:143], s[68:69], 0, v[0:1]
	v_mov_b32_e32 v0, 0
	s_or_b32 s1, s60, 0x800
	s_or_b32 s17, s60, 0x1000
	s_or_b32 s58, s60, 0x1800
	s_mov_b32 s34, -2
	s_mov_b64 s[24:25], 0
	v_add_u32_e32 v163, s59, v6
	v_add_u32_e32 v147, s60, v10
	v_add_u32_e32 v162, s59, v7
	v_add_u32_e32 v152, s59, v8
	v_add_u32_e32 v150, s59, v9
	v_mov_b32_e32 v1, v0
	v_mov_b32_e32 v2, v0
	v_mov_b32_e32 v3, v0
	v_mov_b32_e32 v4, v0
	v_mov_b32_e32 v5, v0
	v_mov_b32_e32 v6, v0
	v_mov_b32_e32 v7, v0
	v_mov_b32_e32 v8, v0
	v_mov_b32_e32 v9, v0
	v_mov_b32_e32 v10, v0
	v_mov_b32_e32 v11, v0
	v_mov_b32_e32 v12, v0
	v_mov_b32_e32 v13, v0
	v_mov_b32_e32 v14, v0
	v_mov_b32_e32 v15, v0
	v_mov_b32_e32 v16, v0
	v_mov_b32_e32 v17, v0
	v_mov_b32_e32 v18, v0
	v_mov_b32_e32 v19, v0
	v_mov_b32_e32 v20, v0
	v_mov_b32_e32 v21, v0
	v_mov_b32_e32 v22, v0
	v_mov_b32_e32 v23, v0
	v_mov_b32_e32 v24, v0
	v_mov_b32_e32 v25, v0
	v_mov_b32_e32 v26, v0
	v_mov_b32_e32 v27, v0
	v_mov_b32_e32 v28, v0
	v_mov_b32_e32 v29, v0
	v_mov_b32_e32 v30, v0
	v_mov_b32_e32 v31, v0
	v_mov_b32_e32 v32, v0
	v_mov_b32_e32 v33, v0
	v_mov_b32_e32 v34, v0
	v_mov_b32_e32 v35, v0
	v_mov_b32_e32 v36, v0
	v_mov_b32_e32 v37, v0
	v_mov_b32_e32 v38, v0
	v_mov_b32_e32 v39, v0
	v_mov_b32_e32 v40, v0
	v_mov_b32_e32 v41, v0
	v_mov_b32_e32 v42, v0
	v_mov_b32_e32 v43, v0
	v_mov_b32_e32 v44, v0
	v_mov_b32_e32 v45, v0
	v_mov_b32_e32 v46, v0
	v_mov_b32_e32 v47, v0
	v_mov_b32_e32 v48, v0
	v_mov_b32_e32 v49, v0
	v_mov_b32_e32 v50, v0
	v_mov_b32_e32 v51, v0
	v_mov_b32_e32 v52, v0
	v_mov_b32_e32 v53, v0
	v_mov_b32_e32 v54, v0
	v_mov_b32_e32 v55, v0
	v_mov_b32_e32 v56, v0
	v_mov_b32_e32 v57, v0
	v_mov_b32_e32 v58, v0
	v_mov_b32_e32 v59, v0
	v_mov_b32_e32 v60, v0
	v_mov_b32_e32 v61, v0
	v_mov_b32_e32 v62, v0
	v_mov_b32_e32 v63, v0
	v_mov_b32_e32 v64, v0
	v_mov_b32_e32 v65, v0
	v_mov_b32_e32 v66, v0
	v_mov_b32_e32 v67, v0
	v_mov_b32_e32 v68, v0
	v_mov_b32_e32 v69, v0
	v_mov_b32_e32 v70, v0
	v_mov_b32_e32 v71, v0
	v_mov_b32_e32 v72, v0
	v_mov_b32_e32 v73, v0
	v_mov_b32_e32 v74, v0
	v_mov_b32_e32 v75, v0
	v_mov_b32_e32 v76, v0
	v_mov_b32_e32 v77, v0
	v_mov_b32_e32 v78, v0
	v_mov_b32_e32 v79, v0
	v_mov_b32_e32 v80, v0
	v_mov_b32_e32 v81, v0
	v_mov_b32_e32 v82, v0
	v_mov_b32_e32 v83, v0
	v_mov_b32_e32 v84, v0
	v_mov_b32_e32 v85, v0
	v_mov_b32_e32 v86, v0
	v_mov_b32_e32 v87, v0
	v_mov_b32_e32 v88, v0
	v_mov_b32_e32 v89, v0
	v_mov_b32_e32 v90, v0
	v_mov_b32_e32 v91, v0
	v_mov_b32_e32 v92, v0
	v_mov_b32_e32 v93, v0
	v_mov_b32_e32 v94, v0
	v_mov_b32_e32 v95, v0
	v_mov_b32_e32 v96, v0
	v_mov_b32_e32 v97, v0
	v_mov_b32_e32 v98, v0
	v_mov_b32_e32 v99, v0
	v_mov_b32_e32 v100, v0
	v_mov_b32_e32 v101, v0
	v_mov_b32_e32 v102, v0
	v_mov_b32_e32 v103, v0
	v_mov_b32_e32 v104, v0
	v_mov_b32_e32 v105, v0
	v_mov_b32_e32 v106, v0
	v_mov_b32_e32 v107, v0
	v_mov_b32_e32 v108, v0
	v_mov_b32_e32 v109, v0
	v_mov_b32_e32 v110, v0
	v_mov_b32_e32 v111, v0
	v_mov_b32_e32 v112, v0
	v_mov_b32_e32 v113, v0
	v_mov_b32_e32 v114, v0
	v_mov_b32_e32 v115, v0
	v_mov_b32_e32 v116, v0
	v_mov_b32_e32 v117, v0
	v_mov_b32_e32 v118, v0
	v_mov_b32_e32 v119, v0
	v_mov_b32_e32 v120, v0
	v_mov_b32_e32 v121, v0
	v_mov_b32_e32 v122, v0
	v_mov_b32_e32 v123, v0
	v_mov_b32_e32 v124, v0
	v_mov_b32_e32 v125, v0
	v_mov_b32_e32 v126, v0
	v_mov_b32_e32 v127, v0
	s_barrier
	v_readlane_b32 s65, v254, 13
	v_readlane_b32 s66, v254, 14
	v_readlane_b32 s67, v254, 15
	v_readlane_b32 s70, v254, 18
	v_readlane_b32 s71, v254, 19
	v_readlane_b32 s72, v254, 20
	v_readlane_b32 s73, v254, 21
	v_readlane_b32 s74, v254, 22
	v_readlane_b32 s75, v254, 23
	v_readlane_b32 s76, v254, 24
	v_readlane_b32 s77, v254, 25
	v_readlane_b32 s78, v254, 26
	v_readlane_b32 s79, v254, 27
	s_nop 0
	s_nop 0
	s_nop 0
	s_nop 0
	s_nop 0
	s_nop 0
	s_nop 0
	s_nop 0
	s_nop 0
	s_nop 0
	s_nop 0
	s_nop 0
	s_nop 0
	s_nop 0
	s_nop 0

.LBB0_811:
	v_add_u32_e32 v155, s53, v17
	v_add_u32_e32 v156, 0x2000, v155
	v_readfirstlane_b32 s58, v155
	v_lshl_add_u64 v[4:5], v[4:5], 0, s[4:5]
	s_mov_b32 m0, s58
	v_readfirstlane_b32 s58, v156
	v_add_u32_e32 v157, 0x8000, v149
	s_waitcnt vmcnt(4)
	s_barrier
	global_load_lds_dwordx4 v[4:5], off
	v_lshl_add_u64 v[4:5], v[6:7], 0, s[4:5]
	s_mov_b32 m0, s58
	v_readfirstlane_b32 s58, v157
	v_add_u32_e32 v158, 0xa000, v149
	global_load_lds_dwordx4 v[4:5], off
	v_lshl_add_u64 v[4:5], v[8:9], 0, s[4:5]
	s_mov_b32 m0, s58
	v_readfirstlane_b32 s58, v158
	v_add_u32_e32 v159, s54, v17
	global_load_lds_dwordx4 v[4:5], off
	v_lshl_add_u64 v[4:5], v[10:11], 0, s[4:5]
	s_mov_b32 m0, s58
	v_readfirstlane_b32 s58, v159
	v_add_u32_e32 v160, 0x2000, v159
	global_load_lds_dwordx4 v[4:5], off
	v_lshl_add_u64 v[4:5], v[12:13], 0, s[4:5]
	s_mov_b32 m0, s58
	v_readfirstlane_b32 s58, v160
	global_load_lds_dwordx4 v[4:5], off
	v_lshl_add_u64 v[4:5], v[14:15], 0, s[4:5]
	s_mov_b32 m0, s58
	v_and_b32_e32 v18, 15, v16
	global_load_lds_dwordx4 v[4:5], off
	v_lshlrev_b32_e32 v5, 2, v16
	v_and_b32_e32 v19, 48, v16
	v_lshlrev_b32_e32 v4, 6, v18
	v_and_b32_e32 v5, 32, v5
	v_bitop3_b32 v4, v4, v5, v19 bitop3:0x36
	v_add_u32_e32 v6, s33, v4
	v_add_u32_e32 v7, s52, v4
	v_add_u32_e32 v8, s53, v4
	v_add_u32_e32 v9, s54, v4
	s_lshl_b32 s61, s17, 13
	v_add_u32_e32 v10, 0, v4
	v_lshlrev_b32_e32 v4, 6, v16
	s_movk_i32 s17, 0x3c0
	v_and_or_b32 v4, v4, s17, v19
	v_xad_u32 v162, v4, v5, 0
	v_lshl_add_u64 v[4:5], s[24:25], 0, v[130:131]
	v_readlane_b32 s64, v254, 12
	v_lshl_add_u64 v[4:5], v[4:5], 0, v[0:1]
	v_readlane_b32 s65, v254, 13
	v_readlane_b32 s72, v254, 20
	v_readlane_b32 s73, v254, 21
	v_lshl_add_u64 v[136:137], s[64:65], 0, v[4:5]
	v_lshl_add_u64 v[4:5], s[24:25], 0, v[134:135]
	v_lshl_add_u64 v[4:5], v[4:5], 0, v[2:3]
	v_lshl_add_u64 v[138:139], s[64:65], 0, v[4:5]
	v_lshl_add_u64 v[4:5], s[34:35], 0, v[130:131]
	v_lshl_add_u64 v[0:1], v[4:5], 0, v[0:1]
	v_lshl_add_u64 v[140:141], s[72:73], 0, v[0:1]
	v_lshl_add_u64 v[0:1], s[34:35], 0, v[134:135]
	s_waitcnt vmcnt(6)
	s_lshl_b32 s58, s0, 6
	v_lshl_add_u64 v[0:1], v[0:1], 0, v[2:3]
	s_and_b32 s60, s58, 0x3000
	v_lshl_add_u64 v[142:143], s[72:73], 0, v[0:1]
	v_mov_b32_e32 v0, 0
	s_or_b32 s17, s61, 0x800
	s_or_b32 s58, s61, 0x1000
	s_or_b32 s59, s61, 0x1800
	s_mov_b32 s34, -2
	s_mov_b64 s[24:25], 0
	v_add_u32_e32 v163, s60, v6
	v_add_u32_e32 v146, s61, v10
	v_add_u32_e32 v161, s60, v7
	v_add_u32_e32 v152, s60, v8
	v_add_u32_e32 v147, s60, v9
	v_mov_b32_e32 v1, v0
	v_mov_b32_e32 v2, v0
	v_mov_b32_e32 v3, v0
	v_mov_b32_e32 v4, v0
	v_mov_b32_e32 v5, v0
	v_mov_b32_e32 v6, v0
	v_mov_b32_e32 v7, v0
	v_mov_b32_e32 v8, v0
	v_mov_b32_e32 v9, v0
	v_mov_b32_e32 v10, v0
	v_mov_b32_e32 v11, v0
	v_mov_b32_e32 v12, v0
	v_mov_b32_e32 v13, v0
	v_mov_b32_e32 v14, v0
	v_mov_b32_e32 v15, v0
	v_mov_b32_e32 v16, v0
	v_mov_b32_e32 v17, v0
	v_mov_b32_e32 v18, v0
	v_mov_b32_e32 v19, v0
	v_mov_b32_e32 v20, v0
	v_mov_b32_e32 v21, v0
	v_mov_b32_e32 v22, v0
	v_mov_b32_e32 v23, v0
	v_mov_b32_e32 v24, v0
	v_mov_b32_e32 v25, v0
	v_mov_b32_e32 v26, v0
	v_mov_b32_e32 v27, v0
	v_mov_b32_e32 v28, v0
	v_mov_b32_e32 v29, v0
	v_mov_b32_e32 v30, v0
	v_mov_b32_e32 v31, v0
	v_mov_b32_e32 v56, v0
	v_mov_b32_e32 v57, v0
	v_mov_b32_e32 v58, v0
	v_mov_b32_e32 v59, v0
	v_mov_b32_e32 v80, v0
	v_mov_b32_e32 v81, v0
	v_mov_b32_e32 v82, v0
	v_mov_b32_e32 v83, v0
	v_mov_b32_e32 v96, v0
	v_mov_b32_e32 v97, v0
	v_mov_b32_e32 v98, v0
	v_mov_b32_e32 v99, v0
	v_mov_b32_e32 v108, v0
	v_mov_b32_e32 v109, v0
	v_mov_b32_e32 v110, v0
	v_mov_b32_e32 v111, v0
	v_mov_b32_e32 v112, v0
	v_mov_b32_e32 v113, v0
	v_mov_b32_e32 v114, v0
	v_mov_b32_e32 v115, v0
	v_mov_b32_e32 v116, v0
	v_mov_b32_e32 v117, v0
	v_mov_b32_e32 v118, v0
	v_mov_b32_e32 v119, v0
	v_mov_b32_e32 v120, v0
	v_mov_b32_e32 v121, v0
	v_mov_b32_e32 v122, v0
	v_mov_b32_e32 v123, v0
	v_mov_b32_e32 v124, v0
	v_mov_b32_e32 v125, v0
	v_mov_b32_e32 v126, v0
	v_mov_b32_e32 v127, v0
	v_mov_b32_e32 v32, v0
	v_mov_b32_e32 v33, v0
	v_mov_b32_e32 v34, v0
	v_mov_b32_e32 v35, v0
	v_mov_b32_e32 v36, v0
	v_mov_b32_e32 v37, v0
	v_mov_b32_e32 v38, v0
	v_mov_b32_e32 v39, v0
	v_mov_b32_e32 v40, v0
	v_mov_b32_e32 v41, v0
	v_mov_b32_e32 v42, v0
	v_mov_b32_e32 v43, v0
	v_mov_b32_e32 v44, v0
	v_mov_b32_e32 v45, v0
	v_mov_b32_e32 v46, v0
	v_mov_b32_e32 v47, v0
	v_mov_b32_e32 v48, v0
	v_mov_b32_e32 v49, v0
	v_mov_b32_e32 v50, v0
	v_mov_b32_e32 v51, v0
	v_mov_b32_e32 v52, v0
	v_mov_b32_e32 v53, v0
	v_mov_b32_e32 v54, v0
	v_mov_b32_e32 v55, v0
	v_mov_b32_e32 v60, v0
	v_mov_b32_e32 v61, v0
	v_mov_b32_e32 v62, v0
	v_mov_b32_e32 v63, v0
	v_mov_b32_e32 v68, v0
	v_mov_b32_e32 v69, v0
	v_mov_b32_e32 v70, v0
	v_mov_b32_e32 v71, v0
	v_mov_b32_e32 v64, v0
	v_mov_b32_e32 v65, v0
	v_mov_b32_e32 v66, v0
	v_mov_b32_e32 v67, v0
	v_mov_b32_e32 v72, v0
	v_mov_b32_e32 v73, v0
	v_mov_b32_e32 v74, v0
	v_mov_b32_e32 v75, v0
	v_mov_b32_e32 v76, v0
	v_mov_b32_e32 v77, v0
	v_mov_b32_e32 v78, v0
	v_mov_b32_e32 v79, v0
	v_mov_b32_e32 v84, v0
	v_mov_b32_e32 v85, v0
	v_mov_b32_e32 v86, v0
	v_mov_b32_e32 v87, v0
	v_mov_b32_e32 v88, v0
	v_mov_b32_e32 v89, v0
	v_mov_b32_e32 v90, v0
	v_mov_b32_e32 v91, v0
	v_mov_b32_e32 v92, v0
	v_mov_b32_e32 v93, v0
	v_mov_b32_e32 v94, v0
	v_mov_b32_e32 v95, v0
	v_mov_b32_e32 v100, v0
	v_mov_b32_e32 v101, v0
	v_mov_b32_e32 v102, v0
	v_mov_b32_e32 v103, v0
	v_mov_b32_e32 v104, v0
	v_mov_b32_e32 v105, v0
	v_mov_b32_e32 v106, v0
	v_mov_b32_e32 v107, v0
	s_barrier
	v_readlane_b32 s66, v254, 14
	v_readlane_b32 s67, v254, 15
	v_readlane_b32 s68, v254, 16
	v_readlane_b32 s69, v254, 17
	v_readlane_b32 s70, v254, 18
	v_readlane_b32 s71, v254, 19
	v_readlane_b32 s74, v254, 22
	v_readlane_b32 s75, v254, 23
	v_readlane_b32 s76, v254, 24
	v_readlane_b32 s77, v254, 25
	v_readlane_b32 s78, v254, 26
	v_readlane_b32 s79, v254, 27
	s_nop 0
	s_nop 0
	s_nop 0
	s_nop 0
	s_nop 0
	s_nop 0
	s_nop 0
	s_nop 0
	s_nop 0
	s_nop 0
	s_nop 0
	s_nop 0
	s_nop 0
	s_nop 0
	s_nop 0

.LBB0_933:
	v_add_u32_e32 v155, s55, v17
	v_add_u32_e32 v156, 0x2000, v155
	v_readfirstlane_b32 s25, v155
	v_lshl_add_u64 v[4:5], v[4:5], 0, s[4:5]
	s_mov_b32 m0, s25
	v_readfirstlane_b32 s25, v156
	v_add_u32_e32 v157, 0x8000, v148
	s_waitcnt vmcnt(4)
	s_barrier
	global_load_lds_dwordx4 v[4:5], off
	v_lshl_add_u64 v[4:5], v[6:7], 0, s[4:5]
	s_mov_b32 m0, s25
	v_readfirstlane_b32 s25, v157
	v_add_u32_e32 v158, 0xa000, v148
	global_load_lds_dwordx4 v[4:5], off
	v_lshl_add_u64 v[4:5], v[8:9], 0, s[4:5]
	s_mov_b32 m0, s25
	v_readfirstlane_b32 s25, v158
	v_add_u32_e32 v159, s56, v17
	global_load_lds_dwordx4 v[4:5], off
	v_lshl_add_u64 v[4:5], v[10:11], 0, s[4:5]
	s_mov_b32 m0, s25
	v_readfirstlane_b32 s25, v159
	v_add_u32_e32 v160, 0x2000, v159
	global_load_lds_dwordx4 v[4:5], off
	v_lshl_add_u64 v[4:5], v[12:13], 0, s[4:5]
	s_mov_b32 m0, s25
	v_readfirstlane_b32 s25, v160
	global_load_lds_dwordx4 v[4:5], off
	v_lshl_add_u64 v[4:5], v[14:15], 0, s[4:5]
	s_mov_b32 m0, s25
	v_and_b32_e32 v18, 15, v16
	global_load_lds_dwordx4 v[4:5], off
	v_lshlrev_b32_e32 v5, 2, v16
	v_and_b32_e32 v19, 48, v16
	v_lshlrev_b32_e32 v4, 6, v18
	v_and_b32_e32 v5, 32, v5
	v_bitop3_b32 v4, v4, v5, v19 bitop3:0x36
	v_add_u32_e32 v6, s53, v4
	v_add_u32_e32 v7, s54, v4
	v_add_u32_e32 v8, s55, v4
	v_add_u32_e32 v9, s56, v4
	s_lshl_b32 s63, s1, 13
	v_add_u32_e32 v10, 0, v4
	v_lshlrev_b32_e32 v4, 6, v16
	s_movk_i32 s1, 0x3c0
	v_and_or_b32 v4, v4, s1, v19
	v_xad_u32 v161, v4, v5, 0
	v_lshl_add_u64 v[4:5], s[90:91], 0, v[130:131]
	v_readlane_b32 s64, v254, 60
	v_lshl_add_u64 v[4:5], v[4:5], 0, v[0:1]
	v_readlane_b32 s76, v253, 8
	v_readlane_b32 s77, v253, 9
	v_readlane_b32 s65, v254, 61
	v_readlane_b32 s66, v254, 62
	v_lshl_add_u64 v[136:137], s[76:77], 0, v[4:5]
	v_lshl_add_u64 v[4:5], s[90:91], 0, v[134:135]
	v_readlane_b32 s67, v254, 63
	v_readlane_b32 s68, v253, 0
	v_readlane_b32 s69, v253, 1
	v_readlane_b32 s70, v253, 2
	v_readlane_b32 s71, v253, 3
	v_readlane_b32 s72, v253, 4
	v_readlane_b32 s73, v253, 5
	v_readlane_b32 s74, v253, 6
	v_readlane_b32 s75, v253, 7
	v_readlane_b32 s78, v253, 10
	v_readlane_b32 s79, v253, 11
	v_lshl_add_u64 v[4:5], v[4:5], 0, v[2:3]
	v_lshl_add_u64 v[138:139], s[76:77], 0, v[4:5]
	v_lshl_add_u64 v[4:5], s[92:93], 0, v[130:131]
	v_readlane_b32 s64, v254, 12
	v_lshl_add_u64 v[0:1], v[4:5], 0, v[0:1]
	v_readlane_b32 s68, v254, 16
	v_readlane_b32 s69, v254, 17
	s_waitcnt vmcnt(6)
	s_lshl_b32 s25, s59, 6
	s_and_b32 s62, s25, 0x3000
	v_lshl_add_u64 v[140:141], s[68:69], 0, v[0:1]
	v_lshl_add_u64 v[0:1], s[92:93], 0, v[134:135]
	v_lshl_add_u64 v[0:1], v[0:1], 0, v[2:3]
	v_lshl_add_u64 v[142:143], s[68:69], 0, v[0:1]
	v_mov_b32_e32 v0, 0
	s_or_b32 s1, s63, 0x800
	s_or_b32 s25, s63, 0x1000
	s_or_b32 s60, s63, 0x1800
	s_mov_b32 s61, -2
	s_mov_b64 s[90:91], 0
	v_add_u32_e32 v163, s62, v6
	v_add_u32_e32 v147, s63, v10
	v_add_u32_e32 v162, s62, v7
	v_add_u32_e32 v152, s62, v8
	v_add_u32_e32 v150, s62, v9
	v_mov_b32_e32 v1, v0
	v_mov_b32_e32 v2, v0
	v_mov_b32_e32 v3, v0
	v_mov_b32_e32 v4, v0
	v_mov_b32_e32 v5, v0
	v_mov_b32_e32 v6, v0
	v_mov_b32_e32 v7, v0
	v_mov_b32_e32 v8, v0
	v_mov_b32_e32 v9, v0
	v_mov_b32_e32 v10, v0
	v_mov_b32_e32 v11, v0
	v_mov_b32_e32 v12, v0
	v_mov_b32_e32 v13, v0
	v_mov_b32_e32 v14, v0
	v_mov_b32_e32 v15, v0
	v_mov_b32_e32 v16, v0
	v_mov_b32_e32 v17, v0
	v_mov_b32_e32 v18, v0
	v_mov_b32_e32 v19, v0
	v_mov_b32_e32 v20, v0
	v_mov_b32_e32 v21, v0
	v_mov_b32_e32 v22, v0
	v_mov_b32_e32 v23, v0
	v_mov_b32_e32 v24, v0
	v_mov_b32_e32 v25, v0
	v_mov_b32_e32 v26, v0
	v_mov_b32_e32 v27, v0
	v_mov_b32_e32 v28, v0
	v_mov_b32_e32 v29, v0
	v_mov_b32_e32 v30, v0
	v_mov_b32_e32 v31, v0
	v_mov_b32_e32 v32, v0
	v_mov_b32_e32 v33, v0
	v_mov_b32_e32 v34, v0
	v_mov_b32_e32 v35, v0
	v_mov_b32_e32 v36, v0
	v_mov_b32_e32 v37, v0
	v_mov_b32_e32 v38, v0
	v_mov_b32_e32 v39, v0
	v_mov_b32_e32 v40, v0
	v_mov_b32_e32 v41, v0
	v_mov_b32_e32 v42, v0
	v_mov_b32_e32 v43, v0
	v_mov_b32_e32 v44, v0
	v_mov_b32_e32 v45, v0
	v_mov_b32_e32 v46, v0
	v_mov_b32_e32 v47, v0
	v_mov_b32_e32 v48, v0
	v_mov_b32_e32 v49, v0
	v_mov_b32_e32 v50, v0
	v_mov_b32_e32 v51, v0
	v_mov_b32_e32 v52, v0
	v_mov_b32_e32 v53, v0
	v_mov_b32_e32 v54, v0
	v_mov_b32_e32 v55, v0
	v_mov_b32_e32 v56, v0
	v_mov_b32_e32 v57, v0
	v_mov_b32_e32 v58, v0
	v_mov_b32_e32 v59, v0
	v_mov_b32_e32 v60, v0
	v_mov_b32_e32 v61, v0
	v_mov_b32_e32 v62, v0
	v_mov_b32_e32 v63, v0
	v_mov_b32_e32 v64, v0
	v_mov_b32_e32 v65, v0
	v_mov_b32_e32 v66, v0
	v_mov_b32_e32 v67, v0
	v_mov_b32_e32 v68, v0
	v_mov_b32_e32 v69, v0
	v_mov_b32_e32 v70, v0
	v_mov_b32_e32 v71, v0
	v_mov_b32_e32 v72, v0
	v_mov_b32_e32 v73, v0
	v_mov_b32_e32 v74, v0
	v_mov_b32_e32 v75, v0
	v_mov_b32_e32 v76, v0
	v_mov_b32_e32 v77, v0
	v_mov_b32_e32 v78, v0
	v_mov_b32_e32 v79, v0
	v_mov_b32_e32 v80, v0
	v_mov_b32_e32 v81, v0
	v_mov_b32_e32 v82, v0
	v_mov_b32_e32 v83, v0
	v_mov_b32_e32 v84, v0
	v_mov_b32_e32 v85, v0
	v_mov_b32_e32 v86, v0
	v_mov_b32_e32 v87, v0
	v_mov_b32_e32 v88, v0
	v_mov_b32_e32 v89, v0
	v_mov_b32_e32 v90, v0
	v_mov_b32_e32 v91, v0
	v_mov_b32_e32 v92, v0
	v_mov_b32_e32 v93, v0
	v_mov_b32_e32 v94, v0
	v_mov_b32_e32 v95, v0
	v_mov_b32_e32 v96, v0
	v_mov_b32_e32 v97, v0
	v_mov_b32_e32 v98, v0
	v_mov_b32_e32 v99, v0
	v_mov_b32_e32 v100, v0
	v_mov_b32_e32 v101, v0
	v_mov_b32_e32 v102, v0
	v_mov_b32_e32 v103, v0
	v_mov_b32_e32 v104, v0
	v_mov_b32_e32 v105, v0
	v_mov_b32_e32 v106, v0
	v_mov_b32_e32 v107, v0
	v_mov_b32_e32 v108, v0
	v_mov_b32_e32 v109, v0
	v_mov_b32_e32 v110, v0
	v_mov_b32_e32 v111, v0
	v_mov_b32_e32 v112, v0
	v_mov_b32_e32 v113, v0
	v_mov_b32_e32 v114, v0
	v_mov_b32_e32 v115, v0
	v_mov_b32_e32 v116, v0
	v_mov_b32_e32 v117, v0
	v_mov_b32_e32 v118, v0
	v_mov_b32_e32 v119, v0
	v_mov_b32_e32 v120, v0
	v_mov_b32_e32 v121, v0
	v_mov_b32_e32 v122, v0
	v_mov_b32_e32 v123, v0
	v_mov_b32_e32 v124, v0
	v_mov_b32_e32 v125, v0
	v_mov_b32_e32 v126, v0
	v_mov_b32_e32 v127, v0
	s_barrier
	v_readlane_b32 s65, v254, 13
	v_readlane_b32 s66, v254, 14
	v_readlane_b32 s67, v254, 15
	v_readlane_b32 s70, v254, 18
	v_readlane_b32 s71, v254, 19
	v_readlane_b32 s72, v254, 20
	v_readlane_b32 s73, v254, 21
	v_readlane_b32 s74, v254, 22
	v_readlane_b32 s75, v254, 23
	v_readlane_b32 s76, v254, 24
	v_readlane_b32 s77, v254, 25
	v_readlane_b32 s78, v254, 26
	v_readlane_b32 s79, v254, 27
	s_nop 0
	s_nop 0

.LBB0_1522:
	v_add_u32_e32 v155, s39, v17
	v_add_u32_e32 v156, 0x2000, v155
	v_readfirstlane_b32 s46, v155
	v_lshl_add_u64 v[4:5], v[4:5], 0, s[4:5]
	s_mov_b32 m0, s46
	v_readfirstlane_b32 s46, v156
	v_add_u32_e32 v157, 0x8000, v148
	s_waitcnt vmcnt(4)
	s_barrier
	global_load_lds_dwordx4 v[4:5], off
	v_lshl_add_u64 v[4:5], v[6:7], 0, s[4:5]
	s_mov_b32 m0, s46
	v_readfirstlane_b32 s46, v157
	v_add_u32_e32 v158, 0xa000, v148
	global_load_lds_dwordx4 v[4:5], off
	v_lshl_add_u64 v[4:5], v[8:9], 0, s[4:5]
	s_mov_b32 m0, s46
	v_readfirstlane_b32 s46, v158
	v_add_u32_e32 v159, s41, v17
	global_load_lds_dwordx4 v[4:5], off
	v_lshl_add_u64 v[4:5], v[10:11], 0, s[4:5]
	s_mov_b32 m0, s46
	v_readfirstlane_b32 s46, v159
	v_add_u32_e32 v160, 0x2000, v159
	global_load_lds_dwordx4 v[4:5], off
	v_lshl_add_u64 v[4:5], v[12:13], 0, s[4:5]
	s_mov_b32 m0, s46
	v_readfirstlane_b32 s46, v160
	global_load_lds_dwordx4 v[4:5], off
	v_lshl_add_u64 v[4:5], v[14:15], 0, s[4:5]
	s_mov_b32 m0, s46
	v_and_b32_e32 v18, 15, v16
	global_load_lds_dwordx4 v[4:5], off
	v_lshlrev_b32_e32 v5, 2, v16
	v_and_b32_e32 v19, 48, v16
	v_lshlrev_b32_e32 v4, 6, v18
	v_and_b32_e32 v5, 32, v5
	v_bitop3_b32 v4, v4, v5, v19 bitop3:0x36
	v_add_u32_e32 v6, s35, v4
	v_add_u32_e32 v7, s38, v4
	v_add_u32_e32 v8, s39, v4
	v_add_u32_e32 v9, s41, v4
	v_add_u32_e32 v10, 0, v4
	v_lshlrev_b32_e32 v4, 6, v16
	v_and_or_b32 v4, v4, s42, v19
	v_xad_u32 v162, v4, v5, 0
	v_lshl_add_u64 v[4:5], s[28:29], 0, v[130:131]
	v_readlane_b32 s56, v254, 12
	v_lshl_add_u64 v[4:5], v[4:5], 0, v[0:1]
	v_readlane_b32 s57, v254, 13
	v_readlane_b32 s64, v254, 20
	v_readlane_b32 s65, v254, 21
	v_lshl_add_u64 v[136:137], s[56:57], 0, v[4:5]
	v_lshl_add_u64 v[4:5], s[28:29], 0, v[134:135]
	v_lshl_add_u64 v[4:5], v[4:5], 0, v[2:3]
	v_lshl_add_u64 v[138:139], s[56:57], 0, v[4:5]
	v_lshl_add_u64 v[4:5], s[30:31], 0, v[130:131]
	v_lshl_add_u64 v[0:1], v[4:5], 0, v[0:1]
	v_lshl_add_u64 v[140:141], s[64:65], 0, v[0:1]
	v_lshl_add_u64 v[0:1], s[30:31], 0, v[134:135]
	s_waitcnt vmcnt(6)
	s_lshl_b32 s46, s0, 6
	v_lshl_add_u64 v[0:1], v[0:1], 0, v[2:3]
	s_and_b32 s48, s46, 0x3000
	s_lshl_b32 s49, s17, 13
	v_lshl_add_u64 v[142:143], s[64:65], 0, v[0:1]
	v_mov_b32_e32 v0, 0
	s_or_b32 s17, s49, 0x800
	s_or_b32 s46, s49, 0x1000
	s_or_b32 s47, s49, 0x1800
	s_mov_b32 s30, -2
	s_mov_b64 s[28:29], 0
	v_add_u32_e32 v163, s48, v6
	v_add_u32_e32 v146, s49, v10
	v_add_u32_e32 v161, s48, v7
	v_add_u32_e32 v152, s48, v8
	v_add_u32_e32 v147, s48, v9
	v_mov_b32_e32 v1, v0
	v_mov_b32_e32 v2, v0
	v_mov_b32_e32 v3, v0
	v_mov_b32_e32 v4, v0
	v_mov_b32_e32 v5, v0
	v_mov_b32_e32 v6, v0
	v_mov_b32_e32 v7, v0
	v_mov_b32_e32 v8, v0
	v_mov_b32_e32 v9, v0
	v_mov_b32_e32 v10, v0
	v_mov_b32_e32 v11, v0
	v_mov_b32_e32 v12, v0
	v_mov_b32_e32 v13, v0
	v_mov_b32_e32 v14, v0
	v_mov_b32_e32 v15, v0
	v_mov_b32_e32 v16, v0
	v_mov_b32_e32 v17, v0
	v_mov_b32_e32 v18, v0
	v_mov_b32_e32 v19, v0
	v_mov_b32_e32 v20, v0
	v_mov_b32_e32 v21, v0
	v_mov_b32_e32 v22, v0
	v_mov_b32_e32 v23, v0
	v_mov_b32_e32 v24, v0
	v_mov_b32_e32 v25, v0
	v_mov_b32_e32 v26, v0
	v_mov_b32_e32 v27, v0
	v_mov_b32_e32 v28, v0
	v_mov_b32_e32 v29, v0
	v_mov_b32_e32 v30, v0
	v_mov_b32_e32 v31, v0
	v_mov_b32_e32 v56, v0
	v_mov_b32_e32 v57, v0
	v_mov_b32_e32 v58, v0
	v_mov_b32_e32 v59, v0
	v_mov_b32_e32 v80, v0
	v_mov_b32_e32 v81, v0
	v_mov_b32_e32 v82, v0
	v_mov_b32_e32 v83, v0
	v_mov_b32_e32 v96, v0
	v_mov_b32_e32 v97, v0
	v_mov_b32_e32 v98, v0
	v_mov_b32_e32 v99, v0
	v_mov_b32_e32 v108, v0
	v_mov_b32_e32 v109, v0
	v_mov_b32_e32 v110, v0
	v_mov_b32_e32 v111, v0
	v_mov_b32_e32 v112, v0
	v_mov_b32_e32 v113, v0
	v_mov_b32_e32 v114, v0
	v_mov_b32_e32 v115, v0
	v_mov_b32_e32 v116, v0
	v_mov_b32_e32 v117, v0
	v_mov_b32_e32 v118, v0
	v_mov_b32_e32 v119, v0
	v_mov_b32_e32 v120, v0
	v_mov_b32_e32 v121, v0
	v_mov_b32_e32 v122, v0
	v_mov_b32_e32 v123, v0
	v_mov_b32_e32 v124, v0
	v_mov_b32_e32 v125, v0
	v_mov_b32_e32 v126, v0
	v_mov_b32_e32 v127, v0
	v_mov_b32_e32 v32, v0
	v_mov_b32_e32 v33, v0
	v_mov_b32_e32 v34, v0
	v_mov_b32_e32 v35, v0
	v_mov_b32_e32 v36, v0
	v_mov_b32_e32 v37, v0
	v_mov_b32_e32 v38, v0
	v_mov_b32_e32 v39, v0
	v_mov_b32_e32 v40, v0
	v_mov_b32_e32 v41, v0
	v_mov_b32_e32 v42, v0
	v_mov_b32_e32 v43, v0
	v_mov_b32_e32 v44, v0
	v_mov_b32_e32 v45, v0
	v_mov_b32_e32 v46, v0
	v_mov_b32_e32 v47, v0
	v_mov_b32_e32 v48, v0
	v_mov_b32_e32 v49, v0
	v_mov_b32_e32 v50, v0
	v_mov_b32_e32 v51, v0
	v_mov_b32_e32 v52, v0
	v_mov_b32_e32 v53, v0
	v_mov_b32_e32 v54, v0
	v_mov_b32_e32 v55, v0
	v_mov_b32_e32 v60, v0
	v_mov_b32_e32 v61, v0
	v_mov_b32_e32 v62, v0
	v_mov_b32_e32 v63, v0
	v_mov_b32_e32 v68, v0
	v_mov_b32_e32 v69, v0
	v_mov_b32_e32 v70, v0
	v_mov_b32_e32 v71, v0
	v_mov_b32_e32 v64, v0
	v_mov_b32_e32 v65, v0
	v_mov_b32_e32 v66, v0
	v_mov_b32_e32 v67, v0
	v_mov_b32_e32 v72, v0
	v_mov_b32_e32 v73, v0
	v_mov_b32_e32 v74, v0
	v_mov_b32_e32 v75, v0
	v_mov_b32_e32 v76, v0
	v_mov_b32_e32 v77, v0
	v_mov_b32_e32 v78, v0
	v_mov_b32_e32 v79, v0
	v_mov_b32_e32 v84, v0
	v_mov_b32_e32 v85, v0
	v_mov_b32_e32 v86, v0
	v_mov_b32_e32 v87, v0
	v_mov_b32_e32 v88, v0
	v_mov_b32_e32 v89, v0
	v_mov_b32_e32 v90, v0
	v_mov_b32_e32 v91, v0
	v_mov_b32_e32 v92, v0
	v_mov_b32_e32 v93, v0
	v_mov_b32_e32 v94, v0
	v_mov_b32_e32 v95, v0
	v_mov_b32_e32 v100, v0
	v_mov_b32_e32 v101, v0
	v_mov_b32_e32 v102, v0
	v_mov_b32_e32 v103, v0
	v_mov_b32_e32 v104, v0
	v_mov_b32_e32 v105, v0
	v_mov_b32_e32 v106, v0
	v_mov_b32_e32 v107, v0
	s_barrier
	v_readlane_b32 s58, v254, 14
	v_readlane_b32 s59, v254, 15
	v_readlane_b32 s60, v254, 16
	v_readlane_b32 s61, v254, 17
	v_readlane_b32 s62, v254, 18
	v_readlane_b32 s63, v254, 19
	v_readlane_b32 s66, v254, 22
	v_readlane_b32 s67, v254, 23
	v_readlane_b32 s68, v254, 24
	v_readlane_b32 s69, v254, 25
	v_readlane_b32 s70, v254, 26
	v_readlane_b32 s71, v254, 27
	s_nop 0
